# P3 late S5 tables: stage bbar/apow/cre/cim of the workgroup in LDS, kc loop reads via ds_read_b128 instead of 20 global loads per step
# speedup vs baseline: 1.0122x; 1.0067x over previous
; DI void s5_tables_late(const Params& p, const int gtid, const int gstr) {
;     unsigned char* ws = p.ws;
;     const float2* apow = (const float2*)(ws + OFF_APOW);
;     const float2* bbar = (const float2*)(ws + OFF_BBAR);
;     const float* cre = p.in[17];
;     const float* cim = p.in[18];
;     bf16_t* kc = (bf16_t*)(ws + OFF_KC);
;     for (int idx = gtid; idx < 32 * 64 * 16 * 2; idx += gstr) {
;         const int g = idx >> 11, tau = (idx >> 5) & 63, c = (idx >> 1) & 15, c20 = (idx & 1) * 8;
;         float sacc[8];
.LBB0_360:
	s_or_b64 exec, exec, s[0:1]
	s_cmpk_gt_u32 s2, 0x7f
	s_cbranch_scc0 .LBB0_370
	v_readlane_b32 s0, v254, 53
	v_mov_b32_e32 v0, v250
	s_add_i32 s0, s0, 0xffff0000
	s_lshr_b32 s74, s0, 11
	s_bfe_u32 s75, s0, 0x60005
	s_lshl_b32 s76, s74, 13
	s_add_u32 s76, s76, 0x211c000
	s_add_u32 s76, s70, s76
	s_addc_u32 s77, s71, 0
	s_mul_i32 s78, s74, 0x41
	s_add_i32 s78, s78, s75
	s_lshl_b32 s78, s78, 9
	s_add_u32 s78, s78, 0x2018000
	s_add_u32 s78, s70, s78
	s_addc_u32 s79, s71, 0
	v_readlane_b32 s80, v254, 22
	v_readlane_b32 s81, v254, 23
	v_readlane_b32 s82, v254, 24
	v_readlane_b32 s83, v254, 25
	v_lshlrev_b32_e32 v116, 4, v250
	v_lshlrev_b32_e32 v117, 3, v250
	v_lshrrev_b32_e32 v118, 5, v250
	s_lshl_b32 s75, s74, 12
	s_add_u32 s80, s80, s75
	s_addc_u32 s81, s81, 0
	s_add_u32 s82, s82, s75
	s_addc_u32 s83, s83, 0
	global_load_dwordx4 v[128:131], v116, s[76:77]
	global_load_dwordx4 v[132:135], v116, s[78:79]
	global_load_dwordx2 v[136:137], v117, s[80:81]
	global_load_dwordx2 v[138:139], v117, s[82:83]
	v_lshlrev_b32_e32 v119, 4, v118
	v_and_b32_e32 v121, 1, v250
	v_bfe_u32 v123, v250, 1, 4
	v_add_u32_e32 v120, v117, v119
	v_add_u32_e32 v119, v116, v119
	v_lshlrev_b32_e32 v121, 6, v121
	v_mul_u32_u24_e32 v122, 0x210, v118
	v_mul_u32_u24_e32 v123, 0x110, v123
	s_waitcnt vmcnt(3)
	ds_write_b128 v116, v[128:131] offset:1024
	s_waitcnt vmcnt(2)
	ds_write_b128 v119, v[132:135] offset:9216
	s_waitcnt vmcnt(1)
	ds_write_b64 v120, v[136:137] offset:17664
	s_waitcnt vmcnt(0)
	ds_write_b64 v120, v[138:139] offset:22016
	s_waitcnt lgkmcnt(0)
	s_barrier
	s_mov_b32 s1, 0x10000
	v_add_u32_e32 v0, s0, v0
	s_lshl_b32 s0, s33, 9
	s_add_i32 s0, s0, 0xffff0000
	v_cmp_gt_i32_e32 vcc, s1, v0
	v_lshlrev_b32_e32 v22, 3, v0
	s_and_saveexec_b64 s[6:7], vcc
	s_cbranch_execz .LBB0_366
	s_add_u32 s8, s70, 0x215c000
	s_addc_u32 s9, s71, 0
	s_lshl_b32 s1, s33, 12
	v_lshlrev_b32_e32 v1, 3, v0
	s_add_i32 s1, s1, 0xfff80000
	s_mov_b64 s[10:11], 0
	v_mov_b32_e32 v3, 0
	s_mov_b64 s[12:13], 0x2018000
	s_mov_b64 s[16:17], 0x211c000
	s_mov_b32 s3, 0x211c000
	s_mov_b32 s34, 0x2018000
	s_mov_b64 s[22:23], 0x211c080
	s_mov_b64 s[24:25], 0x211c100
	s_mov_b64 s[26:27], 0x211c180
	s_mov_b64 s[28:29], 0x200
	s_mov_b32 s35, 0xffff
	v_mov_b32_e32 v23, v0

; DI void s5_tables_late(const Params& p, const int gtid, const int gstr) {
;     ...
;         for (int pp = 0; pp < 64; ++pp) {
;             const float cr = cre[(size_t)(g * 16 + c) * 64 + pp], ci = cim[(size_t)(g * 16 + c) * 64 + pp];
;             const float2 a = apow[((size_t)g * 65 + tau) * 64 + pp];
;             const float wr_ = cr * a.x - ci * a.y, wi_ = cr * a.y + ci * a.x;
;             const float4* bp = (const float4*)(bbar + (size_t)(g * 64 + pp) * 16 + c20);
; #pragma unroll
;             for (int e = 0; e < 4; ++e) { float4 b2 = bp[e]; sacc[2 * e] += wr_ * b2.x - wi_ * b2.y; sacc[2 * e + 1] += wr_ * b2.z - wi_ * b2.w; }
;         }
.LBB0_364:
	ds_read_b128 v[26:29], v123 offset:17664
	ds_read_b128 v[30:33], v123 offset:22016
	ds_read_b128 v[34:37], v122 offset:9216
	ds_read_b128 v[38:41], v121 offset:1024
	ds_read_b128 v[46:49], v121 offset:1040
	ds_read_b128 v[50:53], v121 offset:1056
	ds_read_b128 v[54:57], v121 offset:1152
	ds_read_b128 v[58:61], v121 offset:1168
	ds_read_b128 v[62:65], v121 offset:1184
	ds_read_b128 v[66:69], v122 offset:9232
	ds_read_b128 v[70:73], v121 offset:1280
	ds_read_b128 v[74:77], v121 offset:1296
	ds_read_b128 v[78:81], v121 offset:1312
	ds_read_b128 v[82:85], v121 offset:1408
	ds_read_b128 v[86:89], v121 offset:1424
	ds_read_b128 v[90:93], v121 offset:1440
	ds_read_b128 v[94:97], v121 offset:1072
	ds_read_b128 v[98:101], v121 offset:1200
	ds_read_b128 v[102:105], v121 offset:1328
	ds_read_b128 v[106:109], v121 offset:1456
	s_add_u32 s30, s30, 16
	s_addc_u32 s31, s31, 0
	s_cmpk_eq_i32 s30, 0x100
	v_add_u32_e32 v121, 0x200, v121
	v_add_u32_e32 v122, 32, v122
	v_add_u32_e32 v123, 16, v123
	s_waitcnt lgkmcnt(0)
	v_mov_b32_e32 v112, v38
	v_mov_b32_e32 v42, v33
	v_pk_mul_f32 v[110:111], v[30:31], v[34:35] op_sel:[0,1] op_sel_hi:[0,0]
	v_mov_b32_e32 v2, v29
	v_mov_b32_e32 v113, v40
	v_mov_b32_e32 v40, v39
	v_mov_b32_e32 v38, v46
	v_mov_b32_e32 v39, v48
	v_mov_b32_e32 v48, v47
	v_mov_b32_e32 v46, v50
	v_mov_b32_e32 v47, v52
	v_mov_b32_e32 v52, v51
	v_pk_mul_f32 v[30:31], v[30:31], v[36:37] op_sel:[1,1] op_sel_hi:[1,0]
	v_mov_b32_e32 v50, v54
	v_mov_b32_e32 v51, v56
	v_mov_b32_e32 v56, v55
	v_mov_b32_e32 v54, v58
	v_mov_b32_e32 v55, v60
	v_mov_b32_e32 v60, v59
	v_mov_b32_e32 v58, v62
	v_mov_b32_e32 v59, v64
	v_mov_b32_e32 v64, v63
	v_pk_mul_f32 v[32:33], v[32:33], v[66:67] op_sel:[0,1] op_sel_hi:[0,0]
	v_mov_b32_e32 v62, v70
	v_mov_b32_e32 v63, v72
	v_mov_b32_e32 v72, v71
	v_mov_b32_e32 v70, v74
	v_mov_b32_e32 v71, v76
	v_mov_b32_e32 v76, v75
	v_mov_b32_e32 v74, v78
	v_mov_b32_e32 v75, v80
	v_mov_b32_e32 v80, v79
	v_pk_mul_f32 v[42:43], v[42:43], v[68:69] op_sel:[0,1] op_sel_hi:[0,0]
	v_mov_b32_e32 v78, v82
	v_mov_b32_e32 v79, v84
	v_mov_b32_e32 v84, v83
	v_mov_b32_e32 v82, v86
	v_mov_b32_e32 v83, v88
	v_mov_b32_e32 v88, v87
	v_mov_b32_e32 v86, v90
	v_mov_b32_e32 v87, v92
	v_mov_b32_e32 v92, v91
	v_pk_fma_f32 v[90:91], v[26:27], v[34:35], v[110:111] op_sel_hi:[0,1,1] neg_lo:[0,0,1] neg_hi:[0,0,1]
	v_pk_fma_f32 v[34:35], v[26:27], v[34:35], v[110:111] op_sel_hi:[0,1,1]
	v_pk_fma_f32 v[110:111], v[26:27], v[36:37], v[30:31] op_sel:[1,0,0] neg_lo:[0,0,1] neg_hi:[0,0,1]
	v_pk_fma_f32 v[26:27], v[26:27], v[36:37], v[30:31] op_sel:[1,0,0]
	v_pk_fma_f32 v[30:31], v[28:29], v[66:67], v[32:33] op_sel_hi:[0,1,1] neg_lo:[0,0,1] neg_hi:[0,0,1]
	v_pk_fma_f32 v[28:29], v[28:29], v[66:67], v[32:33] op_sel_hi:[0,1,1]
	v_pk_fma_f32 v[32:33], v[2:3], v[68:69], v[42:43] op_sel_hi:[0,1,1] neg_lo:[0,0,1] neg_hi:[0,0,1]
	v_pk_fma_f32 v[36:37], v[2:3], v[68:69], v[42:43] op_sel_hi:[0,1,1]
	v_mov_b32_e32 v42, v90
	v_mov_b32_e32 v43, v35
	v_pk_mul_f32 v[48:49], v[34:35], v[48:49] op_sel:[1,0]
	v_mov_b32_e32 v68, v110
	v_mov_b32_e32 v69, v27
	v_pk_mul_f32 v[56:57], v[26:27], v[56:57] op_sel:[1,0]
	v_pk_mul_f32 v[60:61], v[26:27], v[60:61] op_sel:[1,0]
	v_pk_mul_f32 v[42:43], v[42:43], v[96:97]
	v_pk_mul_f32 v[40:41], v[34:35], v[40:41] op_sel:[1,0]
	v_pk_mul_f32 v[52:53], v[34:35], v[52:53] op_sel:[1,0]
	v_mul_f32_e32 v34, v90, v94
	v_mul_f32_e32 v66, v35, v95
	v_pk_mul_f32 v[64:65], v[26:27], v[64:65] op_sel:[1,0]
	v_mul_f32_e32 v26, v110, v98
	v_mul_f32_e32 v94, v27, v99
	v_mov_b32_e32 v98, v30
	v_mov_b32_e32 v99, v29
	v_pk_fma_f32 v[38:39], v[90:91], v[38:39], v[48:49] op_sel_hi:[0,1,1] neg_lo:[0,0,1] neg_hi:[0,0,1]
	v_pk_fma_f32 v[48:49], v[50:51], v[110:111], v[56:57] op_sel_hi:[1,0,1] neg_lo:[0,0,1] neg_hi:[0,0,1]
	v_pk_fma_f32 v[50:51], v[110:111], v[54:55], v[60:61] op_sel_hi:[0,1,1] neg_lo:[0,0,1] neg_hi:[0,0,1]
	v_pk_mul_f32 v[54:55], v[68:69], v[100:101]
	v_mov_b32_e32 v35, v42
	v_mov_b32_e32 v67, v43
	v_mov_b32_e32 v114, v32
	v_mov_b32_e32 v115, v37
	v_pk_fma_f32 v[40:41], v[112:113], v[90:91], v[40:41] op_sel_hi:[1,0,1] neg_lo:[0,0,1] neg_hi:[0,0,1]
	v_pk_fma_f32 v[46:47], v[90:91], v[46:47], v[52:53] op_sel_hi:[0,1,1] neg_lo:[0,0,1] neg_hi:[0,0,1]
	v_pk_mul_f32 v[60:61], v[98:99], v[104:105]
	v_mov_b32_e32 v27, v54
	v_mov_b32_e32 v95, v55
	v_pk_add_f32 v[34:35], v[34:35], v[66:67] neg_lo:[0,1] neg_hi:[0,1]
	v_pk_mul_f32 v[72:73], v[28:29], v[72:73] op_sel:[1,0]
	v_pk_mul_f32 v[76:77], v[28:29], v[76:77] op_sel:[1,0]
	v_pk_mul_f32 v[80:81], v[28:29], v[80:81] op_sel:[1,0]
	v_mul_f32_e32 v28, v30, v102
	v_mul_f32_e32 v102, v29, v103
	v_pk_fma_f32 v[52:53], v[110:111], v[58:59], v[64:65] op_sel_hi:[0,1,1] neg_lo:[0,0,1] neg_hi:[0,0,1]
	v_pk_mul_f32 v[68:69], v[114:115], v[108:109]
	v_pk_add_f32 v[16:17], v[16:17], v[40:41]
	v_pk_add_f32 v[18:19], v[18:19], v[38:39]
	v_pk_add_f32 v[20:21], v[20:21], v[46:47]
	v_mov_b32_e32 v29, v60
	v_mov_b32_e32 v103, v61
	v_pk_add_f32 v[26:27], v[26:27], v[94:95] neg_lo:[0,1] neg_hi:[0,1]
	v_pk_add_f32 v[14:15], v[14:15], v[34:35]
	v_pk_mul_f32 v[84:85], v[36:37], v[84:85] op_sel:[1,0]
	v_pk_mul_f32 v[88:89], v[36:37], v[88:89] op_sel:[1,0]
	v_pk_mul_f32 v[92:93], v[36:37], v[92:93] op_sel:[1,0]
	v_mul_f32_e32 v36, v32, v106
	v_mul_f32_e32 v106, v37, v107
	v_pk_fma_f32 v[56:57], v[62:63], v[30:31], v[72:73] op_sel_hi:[1,0,1] neg_lo:[0,0,1] neg_hi:[0,0,1]
	v_pk_fma_f32 v[58:59], v[30:31], v[70:71], v[76:77] op_sel_hi:[0,1,1] neg_lo:[0,0,1] neg_hi:[0,0,1]
	v_pk_fma_f32 v[30:31], v[30:31], v[74:75], v[80:81] op_sel_hi:[0,1,1] neg_lo:[0,0,1] neg_hi:[0,0,1]
	v_mov_b32_e32 v37, v68
	v_mov_b32_e32 v107, v69
	v_pk_add_f32 v[16:17], v[16:17], v[48:49]
	v_pk_add_f32 v[18:19], v[18:19], v[50:51]
	v_pk_add_f32 v[20:21], v[20:21], v[52:53]
	v_pk_add_f32 v[28:29], v[28:29], v[102:103] neg_lo:[0,1] neg_hi:[0,1]
	v_pk_add_f32 v[14:15], v[14:15], v[26:27]
	v_pk_fma_f32 v[62:63], v[78:79], v[32:33], v[84:85] op_sel_hi:[1,0,1] neg_lo:[0,0,1] neg_hi:[0,0,1]
	v_pk_fma_f32 v[64:65], v[32:33], v[82:83], v[88:89] op_sel_hi:[0,1,1] neg_lo:[0,0,1] neg_hi:[0,0,1]
	v_pk_fma_f32 v[32:33], v[32:33], v[86:87], v[92:93] op_sel_hi:[0,1,1] neg_lo:[0,0,1] neg_hi:[0,0,1]
	v_pk_add_f32 v[36:37], v[36:37], v[106:107] neg_lo:[0,1] neg_hi:[0,1]
	v_pk_add_f32 v[16:17], v[16:17], v[56:57]
	v_pk_add_f32 v[18:19], v[18:19], v[58:59]
	v_pk_add_f32 v[20:21], v[20:21], v[30:31]
	v_pk_add_f32 v[14:15], v[14:15], v[28:29]
	v_pk_add_f32 v[16:17], v[16:17], v[62:63]
	v_pk_add_f32 v[18:19], v[18:19], v[64:65]
	v_pk_add_f32 v[20:21], v[20:21], v[32:33]
	v_pk_add_f32 v[14:15], v[14:15], v[36:37]
	s_cbranch_scc0 .LBB0_364
; DI unsigned pk2(float lo, float hi) { f32x2_t v = {lo, hi}; bf16x2_t b = __builtin_convertvector(v, bf16x2_t); return __builtin_bit_cast(unsigned, b); }
; DI void s5_tables_late(const Params& p, const int gtid, const int gstr) {
;     ...
;         *(uint4*)(kc + (((size_t)(g * 64 + tau) * 16 + c) * 16 + c20)) = make_uint4(pk2(sacc[0], sacc[1]), pk2(sacc[2], sacc[3]), pk2(sacc[4], sacc[5]), pk2(sacc[6], sacc[7]));
;     }
	v_and_or_b32 v4, v24, 63, v4
	v_ashrrev_i32_e32 v5, 31, v4
	v_and_b32_e32 v2, 15, v25
	v_lshlrev_b64 v[4:5], 9, v[4:5]
	v_lshl_add_u64 v[4:5], s[8:9], 0, v[4:5]
	v_lshlrev_b32_e32 v2, 5, v2
	v_lshl_add_u64 v[4:5], v[4:5], 0, v[2:3]
	v_lshlrev_b32_e32 v2, 4, v23
	v_add_u32_e32 v23, s0, v23
	v_and_b32_e32 v2, 16, v2
	v_cmp_lt_i32_e32 vcc, s35, v23
	v_cvt_pk_bf16_f32 v6, v16, v17
	v_cvt_pk_bf16_f32 v7, v18, v19
	v_cvt_pk_bf16_f32 v8, v20, v21
	v_cvt_pk_bf16_f32 v9, v14, v15
	v_lshl_add_u64 v[4:5], v[4:5], 0, v[2:3]
	s_or_b64 s[10:11], vcc, s[10:11]
	v_add_u32_e32 v1, s1, v1
	global_store_dwordx4 v[4:5], v[6:9], off
	s_andn2_b64 exec, exec, s[10:11]
	s_cbranch_execnz .LBB0_363
